# adds: QKV kv-latent units run only the non-zero half of K (one K-loop iteration instead of two)
# baseline (speedup 1.0000x reference)
; template <class Epi, class Sched, bool ALIGN_EPI = false, bool SP2 = false>
; __device__ __forceinline__ void gemm_phase(PG8_LAS unsigned char* lds, const Gemm g, const Sched& S, const Epi& E, const int wid_in) {
;     ...
;         const bool has_next = S.next(ui + 1, nxt);
;         const char* nA = has_next ? (const char*)g.A + (size_t)nxt.pm * tstep : cA; const char* nB = has_next ? (const char*)g.Bt + (size_t)nxt.pn * tstep : cB;
; #pragma unroll 1
;         for (int t = 0; t < nt; t += 2) {
;             const bool last = (t == nt - 2);
;             const char* a1 = cA + (size_t)(t + 1) * kstep;
;             const char* a2 = last ? nA : cA + (size_t)(t + 2) * kstep; const char* b2 = last ? nB : cB + (size_t)(t + 2) * kstep;
;     ...
; #pragma unroll
;         for (int a = 0; a < 2; ++a)
; #pragma unroll
;             for (int b = 0; b < 2; ++b)
; #pragma unroll
;                 for (int m = 0; m < 4; ++m)
; #pragma unroll
;                     for (int n = 0; n < 2; ++n) acc[a][b][m][n] = (f32x4){0.f, 0.f, 0.f, 0.f};
.LBB0_266:
	s_ashr_i32 s39, s38, 31
	s_lshl_b64 s[22:23], s[38:39], 17
	v_readlane_b32 s26, v240, 0
	v_readlane_b32 s27, v240, 1
	s_add_u32 s46, s26, s22
	s_addc_u32 s47, s27, s23
	s_and_b64 s[22:23], s[44:45], exec
	s_cselect_b32 s39, s47, s51
	s_cselect_b32 s62, s46, s50
	s_ashr_i32 s43, s42, 31
	s_lshl_b64 s[22:23], s[42:43], 17
	v_readlane_b32 s2, v243, 20
	s_add_u32 s48, s2, s22
	v_readlane_b32 s2, v243, 21
	s_addc_u32 s49, s2, s23
	s_and_b64 s[22:23], s[44:45], exec
	v_mov_b32_e32 v2, 0
	s_cselect_b32 s43, s49, s41
	s_cselect_b32 s16, s48, s40
	s_mov_b64 s[56:57], 0
	s_mov_b64 s[52:53], -1
	s_mov_b64 s[54:55], 0
	s_cmp_lt_u32 s4, 0x80
	s_cbranch_scc1 .Lp4_qunit
	s_mov_b64 s[52:53], 0
	s_mov_b64 s[54:55], -1
.Lp4_qunit:
	v_mov_b32_e32 v3, v2
	v_mov_b32_e32 v4, v2
	v_mov_b32_e32 v5, v2
	v_mov_b32_e32 v6, v2
	v_mov_b32_e32 v7, v2
	v_mov_b32_e32 v8, v2
	v_mov_b32_e32 v9, v2
	v_mov_b32_e32 v10, v2
	v_mov_b32_e32 v11, v2
	v_mov_b32_e32 v12, v2
	v_mov_b32_e32 v13, v2
	v_mov_b32_e32 v14, v2
	v_mov_b32_e32 v15, v2
	v_mov_b32_e32 v16, v2
	v_mov_b32_e32 v17, v2
	v_mov_b32_e32 v18, v2
	v_mov_b32_e32 v19, v2
	v_mov_b32_e32 v20, v2
	v_mov_b32_e32 v21, v2
	v_mov_b32_e32 v22, v2
	v_mov_b32_e32 v23, v2
	v_mov_b32_e32 v24, v2
	v_mov_b32_e32 v25, v2
	v_mov_b32_e32 v26, v2
	v_mov_b32_e32 v27, v2
	v_mov_b32_e32 v28, v2
	v_mov_b32_e32 v29, v2
	v_mov_b32_e32 v30, v2
	v_mov_b32_e32 v31, v2
	v_mov_b32_e32 v32, v2
	v_mov_b32_e32 v33, v2
	v_mov_b32_e32 v74, v2
	v_mov_b32_e32 v75, v2
	v_mov_b32_e32 v76, v2
	v_mov_b32_e32 v77, v2
	v_mov_b32_e32 v78, v2
	v_mov_b32_e32 v79, v2
	v_mov_b32_e32 v80, v2
	v_mov_b32_e32 v81, v2
	v_mov_b32_e32 v106, v2
	v_mov_b32_e32 v107, v2
	v_mov_b32_e32 v108, v2
	v_mov_b32_e32 v109, v2
	v_mov_b32_e32 v110, v2
	v_mov_b32_e32 v111, v2
	v_mov_b32_e32 v112, v2
	v_mov_b32_e32 v113, v2
	v_mov_b32_e32 v114, v2
	v_mov_b32_e32 v115, v2
	v_mov_b32_e32 v116, v2
	v_mov_b32_e32 v117, v2
	v_mov_b32_e32 v118, v2
	v_mov_b32_e32 v119, v2
	v_mov_b32_e32 v120, v2
	v_mov_b32_e32 v121, v2
	v_mov_b32_e32 v122, v2
	v_mov_b32_e32 v123, v2
	v_mov_b32_e32 v124, v2
	v_mov_b32_e32 v125, v2
	v_mov_b32_e32 v126, v2
	v_mov_b32_e32 v127, v2
	v_mov_b32_e32 v128, v2
	v_mov_b32_e32 v129, v2
	v_mov_b32_e32 v34, v2
	v_mov_b32_e32 v35, v2
	v_mov_b32_e32 v36, v2
	v_mov_b32_e32 v37, v2
	v_mov_b32_e32 v38, v2
	v_mov_b32_e32 v39, v2
	v_mov_b32_e32 v40, v2
	v_mov_b32_e32 v41, v2
	v_mov_b32_e32 v42, v2
	v_mov_b32_e32 v43, v2
	v_mov_b32_e32 v44, v2
	v_mov_b32_e32 v45, v2
	v_mov_b32_e32 v46, v2
	v_mov_b32_e32 v47, v2
	v_mov_b32_e32 v48, v2
	v_mov_b32_e32 v49, v2
	v_mov_b32_e32 v50, v2
	v_mov_b32_e32 v51, v2
	v_mov_b32_e32 v52, v2
	v_mov_b32_e32 v53, v2
	v_mov_b32_e32 v54, v2
	v_mov_b32_e32 v55, v2
	v_mov_b32_e32 v56, v2
	v_mov_b32_e32 v57, v2
	v_mov_b32_e32 v58, v2
	v_mov_b32_e32 v59, v2
	v_mov_b32_e32 v60, v2
	v_mov_b32_e32 v61, v2
	v_mov_b32_e32 v62, v2
	v_mov_b32_e32 v63, v2
	v_mov_b32_e32 v64, v2
	v_mov_b32_e32 v65, v2
	v_mov_b32_e32 v130, v2
	v_mov_b32_e32 v131, v2
	v_mov_b32_e32 v132, v2
	v_mov_b32_e32 v133, v2
	v_mov_b32_e32 v134, v2
	v_mov_b32_e32 v135, v2
	v_mov_b32_e32 v136, v2
	v_mov_b32_e32 v137, v2
	v_mov_b32_e32 v138, v2
	v_mov_b32_e32 v139, v2
	v_mov_b32_e32 v140, v2
	v_mov_b32_e32 v141, v2
	v_mov_b32_e32 v142, v2
	v_mov_b32_e32 v143, v2
	v_mov_b32_e32 v144, v2
	v_mov_b32_e32 v145, v2
	v_mov_b32_e32 v146, v2
	v_mov_b32_e32 v147, v2
	v_mov_b32_e32 v148, v2
	v_mov_b32_e32 v149, v2
	v_mov_b32_e32 v150, v2
	v_mov_b32_e32 v151, v2
	v_mov_b32_e32 v152, v2
	v_mov_b32_e32 v153, v2
	v_mov_b32_e32 v154, v2
	v_mov_b32_e32 v155, v2
	v_mov_b32_e32 v156, v2
	v_mov_b32_e32 v157, v2
	v_mov_b32_e32 v158, v2
	v_mov_b32_e32 v159, v2
	v_mov_b32_e32 v160, v2
	v_mov_b32_e32 v161, v2
